# final rmsnorm fused into the last out-projection epilogue: residual kept in registers, row statistics exchanged through a per-group counter, normalized output stored directly (no final phase, no last
# speedup vs baseline: 1.2187x; 1.0099x over previous
.LBB0_532:
	s_or_b64 exec, exec, s[0:1]
	v_readlane_b32 s20, v255, 5
	v_readlane_b32 s21, v255, 6
	s_mov_b64 s[0:1], 0x1200000
	s_mov_b64 s[6:7], 0x9f7b000
	s_mov_b64 s[54:55], 0x517b000
	s_mov_b64 s[8:9], 0x217b000
	s_mov_b64 s[10:11], 0xb77b000
	s_mov_b64 s[52:53], 0xb83b000
	s_mov_b64 s[12:13], 0xb89b000
	s_mov_b64 s[4:5], 0x1e40000
	s_andn2_b64 vcc, exec, s[20:21]
	s_waitcnt lgkmcnt(0)
	s_barrier
	s_cbranch_vccz .Lfz_skip
	s_cmp_lg_u32 s86, 3
	s_cbranch_scc1 .LBB0_630
	v_mov_b32_e32 v200, 0x23808
	ds_read_b32 v200, v200
	s_waitcnt lgkmcnt(0)
	s_nop 0
	v_readfirstlane_b32 s19, v200
	s_cmp_eq_u32 s19, 0
	s_cbranch_scc1 .LBB0_630
	s_endpgm
.Lfz_skip:
	s_add_u32 s19, s28, s0
	s_addc_u32 s23, s29, s1
	s_lshl_b64 s[20:21], s[86:87], 21
	s_add_u32 s20, s19, s20
	s_addc_u32 s21, s23, s21
	s_add_u32 s24, s28, s6
	s_addc_u32 s25, s29, s7
	s_add_u32 s6, s28, s54
	s_addc_u32 s7, s29, s55
	s_add_u32 s8, s28, s8
	s_addc_u32 s9, s29, s9
	s_add_u32 s87, s28, s10
	s_addc_u32 s19, s29, s11
	s_add_u32 s10, s28, s52
	s_addc_u32 s11, s29, s53
	s_add_u32 s12, s28, s12
	s_addc_u32 s13, s29, s13
	s_add_u32 s33, s28, s4
	s_addc_u32 s63, s29, s5
	s_cmp_lg_u32 s86, 3
	s_cselect_b64 s[88:89], -1, 0
	s_lshl_b32 s4, s86, 12
	s_addk_i32 s4, 0x1000
	v_readlane_b32 s36, v254, 16
	s_cmp_lg_u32 s86, 0
	v_readlane_b32 s48, v254, 28
	s_cselect_b64 s[90:91], -1, 0
	v_readlane_b32 s49, v254, 29
	s_add_u32 s92, s48, s4
	s_addc_u32 s93, s49, 0
	v_readlane_b32 s4, v255, 31
	v_readlane_b32 s5, v255, 32
	s_add_u32 s70, s4, s0
	s_addc_u32 s71, s5, s1
	s_mov_b32 s84, s85
	v_readlane_b32 s37, v254, 17
	v_readlane_b32 s38, v254, 18
	v_readlane_b32 s39, v254, 19
	v_readlane_b32 s40, v254, 20
	v_readlane_b32 s41, v254, 21
	v_readlane_b32 s42, v254, 22
	v_readlane_b32 s43, v254, 23
	v_readlane_b32 s44, v254, 24
	v_readlane_b32 s45, v254, 25
	v_readlane_b32 s46, v254, 26
	v_readlane_b32 s47, v254, 27
	v_readlane_b32 s50, v254, 30
	v_readlane_b32 s51, v254, 31
	s_branch .LBB0_535

.Loe_x_done:
	s_lshl_b32 s47, s46, 12
	s_lshl_b32 s100, s94, 2
	s_add_u32 s47, s47, s100
	s_add_u32 s44, s44, s47
	s_addc_u32 s45, s45, 0
	s_lshl_b32 s47, s96, 12
	s_add_u32 s47, s47, s100
	s_add_u32 s48, s8, s47
	s_addc_u32 s49, s9, 0
	s_lshr_b32 s47, s47, 1
	s_add_u32 s50, s6, s47
	s_addc_u32 s51, s7, 0
	s_lshl_b32 s47, s96, 5
	s_lshl_b32 s100, s23, 3
	s_add_u32 s47, s47, s100
	s_add_u32 s42, s87, s47
	s_addc_u32 s43, s19, 0
	v_mov_b32_e32 v216, 0
	v_mov_b32_e32 v217, 0
	v_mov_b32_e32 v218, 0
	v_mov_b32_e32 v219, 0
	v_mov_b32_e32 v220, 0
	v_mov_b32_e32 v221, 0
	v_mov_b32_e32 v222, 0
	v_mov_b32_e32 v223, 0
	v_mov_b32_e32 v224, 0
	v_mov_b32_e32 v225, 0
	v_mov_b32_e32 v226, 0
	v_mov_b32_e32 v227, 0
	v_mov_b32_e32 v228, 0
	v_mov_b32_e32 v229, 0
	v_mov_b32_e32 v230, 0
	v_mov_b32_e32 v231, 0
	v_mov_b32_e32 v203, 0x23808
	ds_read_b32 v203, v203
	s_waitcnt lgkmcnt(0)
	s_nop 0
	v_readfirstlane_b32 s101, v203
	s_cmp_eq_u32 s86, 3
	s_cselect_b32 s101, s101, 0
	s_cmp_lg_u32 s101, 0
	s_cbranch_scc1 .Lof_start
	s_add_u32 s36, s44, 0x0
	s_addc_u32 s37, s45, 0
	global_load_dwordx4 v[128:131], v232, s[36:37]
	global_load_dwordx4 v[132:135], v233, s[36:37]
	global_load_dwordx4 v[136:139], v234, s[36:37]
	global_load_dwordx4 v[140:143], v235, s[36:37]
	s_add_u32 s36, s44, 0x10000
	s_addc_u32 s37, s45, 0
	global_load_dwordx4 v[144:147], v232, s[36:37]
	global_load_dwordx4 v[148:151], v233, s[36:37]
	global_load_dwordx4 v[152:155], v234, s[36:37]
	global_load_dwordx4 v[156:159], v235, s[36:37]
	s_add_u32 s36, s44, 0x80000
	s_addc_u32 s37, s45, 0
	global_load_dwordx4 v[160:163], v232, s[36:37]
	global_load_dwordx4 v[164:167], v233, s[36:37]
	global_load_dwordx4 v[168:171], v234, s[36:37]
	global_load_dwordx4 v[172:175], v235, s[36:37]
	s_waitcnt lgkmcnt(0)
	v_mov_b32_e32 v192, v184
	v_mov_b32_e32 v193, v186
	v_mov_b32_e32 v194, v188
	v_mov_b32_e32 v195, v190
	v_mov_b32_e32 v184, v185
	v_mov_b32_e32 v185, v187
	v_mov_b32_e32 v186, v189
	v_mov_b32_e32 v187, v191
	v_pk_mul_f32 v[48:49], v[48:49], v[176:177] op_sel_hi:[1,0]
	v_pk_mul_f32 v[50:51], v[50:51], v[176:177] op_sel_hi:[1,0]
	v_pk_mul_f32 v[116:117], v[116:117], v[176:177] op_sel_hi:[1,0]
	v_pk_mul_f32 v[118:119], v[118:119], v[176:177] op_sel_hi:[1,0]
	v_pk_mul_f32 v[124:125], v[124:125], v[176:177] op_sel_hi:[1,0]
	v_pk_mul_f32 v[126:127], v[126:127], v[176:177] op_sel_hi:[1,0]
	v_pk_mul_f32 v[108:109], v[108:109], v[176:177] op_sel_hi:[1,0]
	v_pk_mul_f32 v[110:111], v[110:111], v[176:177] op_sel_hi:[1,0]
	ds_write_b128 v198, v[48:51]
	ds_write_b128 v198, v[116:119] offset:64
	ds_write_b128 v198, v[124:127] offset:128
	ds_write_b128 v198, v[108:111] offset:192
	ds_read_b128 v[200:203], v242
	ds_read_b128 v[204:207], v242 offset:1088
	ds_read_b128 v[208:211], v242 offset:2176
	ds_read_b128 v[212:215], v242 offset:3264
	v_pk_mul_f32 v[60:61], v[60:61], v[178:179] op_sel_hi:[1,0]
	v_pk_mul_f32 v[62:63], v[62:63], v[178:179] op_sel_hi:[1,0]
	v_pk_mul_f32 v[88:89], v[88:89], v[178:179] op_sel_hi:[1,0]
	v_pk_mul_f32 v[90:91], v[90:91], v[178:179] op_sel_hi:[1,0]
	v_pk_mul_f32 v[120:121], v[120:121], v[178:179] op_sel_hi:[1,0]
	v_pk_mul_f32 v[122:123], v[122:123], v[178:179] op_sel_hi:[1,0]
	v_pk_mul_f32 v[100:101], v[100:101], v[178:179] op_sel_hi:[1,0]
	v_pk_mul_f32 v[102:103], v[102:103], v[178:179] op_sel_hi:[1,0]
	ds_write_b128 v198, v[60:63]
	ds_write_b128 v198, v[88:91] offset:64
	ds_write_b128 v198, v[120:123] offset:128
	ds_write_b128 v198, v[100:103] offset:192
	s_waitcnt lgkmcnt(4)
	s_waitcnt vmcnt(8)
	v_pk_fma_f32 v[128:129], v[200:201], v[192:193], v[128:129]
	v_pk_fma_f32 v[130:131], v[202:203], v[194:195], v[130:131]
	v_pk_fma_f32 v[132:133], v[204:205], v[192:193], v[132:133]
	v_pk_fma_f32 v[134:135], v[206:207], v[194:195], v[134:135]
	v_pk_fma_f32 v[136:137], v[208:209], v[192:193], v[136:137]
	v_pk_fma_f32 v[138:139], v[210:211], v[194:195], v[138:139]
	v_pk_fma_f32 v[140:141], v[212:213], v[192:193], v[140:141]
	v_pk_fma_f32 v[142:143], v[214:215], v[194:195], v[142:143]
	s_add_u32 s38, s48, 0x0
	s_addc_u32 s39, s49, 0
	v_fma_f32 v216, v128, v128, v216
	v_fma_f32 v216, v129, v129, v216
	v_fma_f32 v216, v130, v130, v216
	v_fma_f32 v216, v131, v131, v216
	global_store_dwordx4 v232, v[128:131], s[38:39]
	v_fma_f32 v217, v132, v132, v217
	v_fma_f32 v217, v133, v133, v217
	v_fma_f32 v217, v134, v134, v217
	v_fma_f32 v217, v135, v135, v217
	global_store_dwordx4 v233, v[132:135], s[38:39]
	v_fma_f32 v218, v136, v136, v218
	v_fma_f32 v218, v137, v137, v218
	v_fma_f32 v218, v138, v138, v218
	v_fma_f32 v218, v139, v139, v218
	global_store_dwordx4 v234, v[136:139], s[38:39]
	v_fma_f32 v219, v140, v140, v219
	v_fma_f32 v219, v141, v141, v219
	v_fma_f32 v219, v142, v142, v219
	v_fma_f32 v219, v143, v143, v219
	global_store_dwordx4 v235, v[140:143], s[38:39]
	s_cmp_eq_u32 s86, 3
	s_cbranch_scc1 .Loe_nxg0
	s_add_u32 s40, s50, 0x0
	s_addc_u32 s41, s51, 0
	v_pk_mul_f32 v[200:201], v[128:129], v[184:185]
	v_pk_mul_f32 v[202:203], v[130:131], v[186:187]
	v_pk_mul_f32 v[204:205], v[132:133], v[184:185]
	v_pk_mul_f32 v[206:207], v[134:135], v[186:187]
	v_pk_mul_f32 v[208:209], v[136:137], v[184:185]
	v_pk_mul_f32 v[210:211], v[138:139], v[186:187]
	v_pk_mul_f32 v[212:213], v[140:141], v[184:185]
	v_pk_mul_f32 v[214:215], v[142:143], v[186:187]
	v_cvt_pk_bf16_f32 v200, v200, v201
	v_cvt_pk_bf16_f32 v201, v202, v203
	v_cvt_pk_bf16_f32 v204, v204, v205
	v_cvt_pk_bf16_f32 v205, v206, v207
	v_cvt_pk_bf16_f32 v208, v208, v209
	v_cvt_pk_bf16_f32 v209, v210, v211
	v_cvt_pk_bf16_f32 v212, v212, v213
	v_cvt_pk_bf16_f32 v213, v214, v215
	global_store_dwordx2 v236, v[200:201], s[40:41]
	global_store_dwordx2 v237, v[204:205], s[40:41]
	global_store_dwordx2 v238, v[208:209], s[40:41]
	global_store_dwordx2 v239, v[212:213], s[40:41]

.Lof_start:
	s_add_u32 s36, s44, 0x0
	s_addc_u32 s37, s45, 0
	global_load_dwordx4 v[128:131], v232, s[36:37]
	global_load_dwordx4 v[132:135], v233, s[36:37]
	global_load_dwordx4 v[136:139], v234, s[36:37]
	global_load_dwordx4 v[140:143], v235, s[36:37]
	s_add_u32 s36, s44, 0x10000
	s_addc_u32 s37, s45, 0
	global_load_dwordx4 v[144:147], v232, s[36:37]
	global_load_dwordx4 v[148:151], v233, s[36:37]
	global_load_dwordx4 v[152:155], v234, s[36:37]
	global_load_dwordx4 v[156:159], v235, s[36:37]
	s_add_u32 s36, s44, 0x80000
	s_addc_u32 s37, s45, 0
	global_load_dwordx4 v[160:163], v232, s[36:37]
	global_load_dwordx4 v[164:167], v233, s[36:37]
	global_load_dwordx4 v[168:171], v234, s[36:37]
	global_load_dwordx4 v[172:175], v235, s[36:37]
	s_waitcnt lgkmcnt(0)
	v_mov_b32_e32 v192, v184
	v_mov_b32_e32 v193, v186
	v_mov_b32_e32 v194, v188
	v_mov_b32_e32 v195, v190
	v_mov_b32_e32 v184, v185
	v_mov_b32_e32 v185, v187
	v_mov_b32_e32 v186, v189
	v_mov_b32_e32 v187, v191
	v_pk_mul_f32 v[48:49], v[48:49], v[176:177] op_sel_hi:[1,0]
	v_pk_mul_f32 v[50:51], v[50:51], v[176:177] op_sel_hi:[1,0]
	v_pk_mul_f32 v[116:117], v[116:117], v[176:177] op_sel_hi:[1,0]
	v_pk_mul_f32 v[118:119], v[118:119], v[176:177] op_sel_hi:[1,0]
	v_pk_mul_f32 v[124:125], v[124:125], v[176:177] op_sel_hi:[1,0]
	v_pk_mul_f32 v[126:127], v[126:127], v[176:177] op_sel_hi:[1,0]
	v_pk_mul_f32 v[108:109], v[108:109], v[176:177] op_sel_hi:[1,0]
	v_pk_mul_f32 v[110:111], v[110:111], v[176:177] op_sel_hi:[1,0]
	ds_write_b128 v198, v[48:51]
	ds_write_b128 v198, v[116:119] offset:64
	ds_write_b128 v198, v[124:127] offset:128
	ds_write_b128 v198, v[108:111] offset:192
	ds_read_b128 v[200:203], v242
	ds_read_b128 v[204:207], v242 offset:1088
	ds_read_b128 v[208:211], v242 offset:2176
	ds_read_b128 v[212:215], v242 offset:3264
	v_pk_mul_f32 v[60:61], v[60:61], v[178:179] op_sel_hi:[1,0]
	v_pk_mul_f32 v[62:63], v[62:63], v[178:179] op_sel_hi:[1,0]
	v_pk_mul_f32 v[88:89], v[88:89], v[178:179] op_sel_hi:[1,0]
	v_pk_mul_f32 v[90:91], v[90:91], v[178:179] op_sel_hi:[1,0]
	v_pk_mul_f32 v[120:121], v[120:121], v[178:179] op_sel_hi:[1,0]
	v_pk_mul_f32 v[122:123], v[122:123], v[178:179] op_sel_hi:[1,0]
	v_pk_mul_f32 v[100:101], v[100:101], v[178:179] op_sel_hi:[1,0]
	v_pk_mul_f32 v[102:103], v[102:103], v[178:179] op_sel_hi:[1,0]
	ds_write_b128 v198, v[60:63]
	ds_write_b128 v198, v[88:91] offset:64
	ds_write_b128 v198, v[120:123] offset:128
	ds_write_b128 v198, v[100:103] offset:192
	s_waitcnt lgkmcnt(4)
	s_waitcnt vmcnt(8)
	v_pk_fma_f32 v[48:49], v[200:201], v[192:193], v[128:129]
	v_pk_fma_f32 v[50:51], v[202:203], v[194:195], v[130:131]
	v_pk_fma_f32 v[116:117], v[204:205], v[192:193], v[132:133]
	v_pk_fma_f32 v[118:119], v[206:207], v[194:195], v[134:135]
	v_pk_fma_f32 v[124:125], v[208:209], v[192:193], v[136:137]
	v_pk_fma_f32 v[126:127], v[210:211], v[194:195], v[138:139]
	v_pk_fma_f32 v[108:109], v[212:213], v[192:193], v[140:141]
	v_pk_fma_f32 v[110:111], v[214:215], v[194:195], v[142:143]
	v_fma_f32 v216, v48, v48, v216
	v_fma_f32 v216, v49, v49, v216
	v_fma_f32 v216, v50, v50, v216
	v_fma_f32 v216, v51, v51, v216
	v_fma_f32 v217, v116, v116, v217
	v_fma_f32 v217, v117, v117, v217
	v_fma_f32 v217, v118, v118, v217
	v_fma_f32 v217, v119, v119, v217
	v_fma_f32 v218, v124, v124, v218
	v_fma_f32 v218, v125, v125, v218
	v_fma_f32 v218, v126, v126, v218
	v_fma_f32 v218, v127, v127, v218
	v_fma_f32 v219, v108, v108, v219
	v_fma_f32 v219, v109, v109, v219
	v_fma_f32 v219, v110, v110, v219
	v_fma_f32 v219, v111, v111, v219
	s_nop 1
	s_add_u32 s36, s44, 0x90000
	s_addc_u32 s37, s45, 0
	global_load_dwordx4 v[128:131], v232, s[36:37]
	global_load_dwordx4 v[132:135], v233, s[36:37]
	global_load_dwordx4 v[136:139], v234, s[36:37]
	global_load_dwordx4 v[140:143], v235, s[36:37]
	ds_read_b128 v[200:203], v242
	ds_read_b128 v[204:207], v242 offset:1088
	ds_read_b128 v[208:211], v242 offset:2176
	ds_read_b128 v[212:215], v242 offset:3264
	v_pk_mul_f32 v[52:53], v[52:53], v[180:181] op_sel_hi:[1,0]
	v_pk_mul_f32 v[54:55], v[54:55], v[180:181] op_sel_hi:[1,0]
	v_pk_mul_f32 v[84:85], v[84:85], v[180:181] op_sel_hi:[1,0]
	v_pk_mul_f32 v[86:87], v[86:87], v[180:181] op_sel_hi:[1,0]
	v_pk_mul_f32 v[112:113], v[112:113], v[180:181] op_sel_hi:[1,0]
	v_pk_mul_f32 v[114:115], v[114:115], v[180:181] op_sel_hi:[1,0]
	v_pk_mul_f32 v[96:97], v[96:97], v[180:181] op_sel_hi:[1,0]
	v_pk_mul_f32 v[98:99], v[98:99], v[180:181] op_sel_hi:[1,0]
	ds_write_b128 v198, v[52:55]
	ds_write_b128 v198, v[84:87] offset:64
	ds_write_b128 v198, v[112:115] offset:128
	ds_write_b128 v198, v[96:99] offset:192
	s_waitcnt lgkmcnt(4)
	s_waitcnt vmcnt(8)
	v_pk_fma_f32 v[60:61], v[200:201], v[192:193], v[144:145]
	v_pk_fma_f32 v[62:63], v[202:203], v[194:195], v[146:147]
	v_pk_fma_f32 v[88:89], v[204:205], v[192:193], v[148:149]
	v_pk_fma_f32 v[90:91], v[206:207], v[194:195], v[150:151]
	v_pk_fma_f32 v[120:121], v[208:209], v[192:193], v[152:153]
	v_pk_fma_f32 v[122:123], v[210:211], v[194:195], v[154:155]
	v_pk_fma_f32 v[100:101], v[212:213], v[192:193], v[156:157]
	v_pk_fma_f32 v[102:103], v[214:215], v[194:195], v[158:159]
	v_fma_f32 v220, v60, v60, v220
	v_fma_f32 v220, v61, v61, v220
	v_fma_f32 v220, v62, v62, v220
	v_fma_f32 v220, v63, v63, v220
	v_fma_f32 v221, v88, v88, v221
	v_fma_f32 v221, v89, v89, v221
	v_fma_f32 v221, v90, v90, v221
	v_fma_f32 v221, v91, v91, v221
	v_fma_f32 v222, v120, v120, v222
	v_fma_f32 v222, v121, v121, v222
	v_fma_f32 v222, v122, v122, v222
	v_fma_f32 v222, v123, v123, v222
	v_fma_f32 v223, v100, v100, v223
	v_fma_f32 v223, v101, v101, v223
	v_fma_f32 v223, v102, v102, v223
	v_fma_f32 v223, v103, v103, v223
	s_nop 1
	s_add_u32 s36, s44, 0x200
	s_addc_u32 s37, s45, 0
	global_load_dwordx4 v[144:147], v232, s[36:37]
	global_load_dwordx4 v[148:151], v233, s[36:37]
	global_load_dwordx4 v[152:155], v234, s[36:37]
	global_load_dwordx4 v[156:159], v235, s[36:37]
	ds_read_b128 v[200:203], v242
	ds_read_b128 v[204:207], v242 offset:1088
	ds_read_b128 v[208:211], v242 offset:2176
	ds_read_b128 v[212:215], v242 offset:3264
	v_pk_mul_f32 v[40:41], v[40:41], v[182:183] op_sel_hi:[1,0]
	v_pk_mul_f32 v[42:43], v[42:43], v[182:183] op_sel_hi:[1,0]
	v_pk_mul_f32 v[76:77], v[76:77], v[182:183] op_sel_hi:[1,0]
	v_pk_mul_f32 v[78:79], v[78:79], v[182:183] op_sel_hi:[1,0]
	v_pk_mul_f32 v[104:105], v[104:105], v[182:183] op_sel_hi:[1,0]
	v_pk_mul_f32 v[106:107], v[106:107], v[182:183] op_sel_hi:[1,0]
	v_pk_mul_f32 v[92:93], v[92:93], v[182:183] op_sel_hi:[1,0]
	v_pk_mul_f32 v[94:95], v[94:95], v[182:183] op_sel_hi:[1,0]
	ds_write_b128 v198, v[40:43]
	ds_write_b128 v198, v[76:79] offset:64
	ds_write_b128 v198, v[104:107] offset:128
	ds_write_b128 v198, v[92:95] offset:192
	s_waitcnt lgkmcnt(4)
	s_waitcnt vmcnt(8)
	v_pk_fma_f32 v[52:53], v[200:201], v[192:193], v[160:161]
	v_pk_fma_f32 v[54:55], v[202:203], v[194:195], v[162:163]
	v_pk_fma_f32 v[84:85], v[204:205], v[192:193], v[164:165]
	v_pk_fma_f32 v[86:87], v[206:207], v[194:195], v[166:167]
	v_pk_fma_f32 v[112:113], v[208:209], v[192:193], v[168:169]
	v_pk_fma_f32 v[114:115], v[210:211], v[194:195], v[170:171]
	v_pk_fma_f32 v[96:97], v[212:213], v[192:193], v[172:173]
	v_pk_fma_f32 v[98:99], v[214:215], v[194:195], v[174:175]
	v_fma_f32 v224, v52, v52, v224
	v_fma_f32 v224, v53, v53, v224
	v_fma_f32 v224, v54, v54, v224
	v_fma_f32 v224, v55, v55, v224
	v_fma_f32 v225, v84, v84, v225
	v_fma_f32 v225, v85, v85, v225
	v_fma_f32 v225, v86, v86, v225
	v_fma_f32 v225, v87, v87, v225
	v_fma_f32 v226, v112, v112, v226
	v_fma_f32 v226, v113, v113, v226
	v_fma_f32 v226, v114, v114, v226
	v_fma_f32 v226, v115, v115, v226
	v_fma_f32 v227, v96, v96, v227
	v_fma_f32 v227, v97, v97, v227
	v_fma_f32 v227, v98, v98, v227
	v_fma_f32 v227, v99, v99, v227
	s_nop 1
	s_add_u32 s36, s44, 0x10200
	s_addc_u32 s37, s45, 0
	global_load_dwordx4 v[160:163], v232, s[36:37]
	global_load_dwordx4 v[164:167], v233, s[36:37]
	global_load_dwordx4 v[168:171], v234, s[36:37]
	global_load_dwordx4 v[172:175], v235, s[36:37]
	ds_read_b128 v[200:203], v242
	ds_read_b128 v[204:207], v242 offset:1088
	ds_read_b128 v[208:211], v242 offset:2176
	ds_read_b128 v[212:215], v242 offset:3264
	v_pk_mul_f32 v[80:81], v[80:81], v[176:177] op_sel_hi:[1,0]
	v_pk_mul_f32 v[82:83], v[82:83], v[176:177] op_sel_hi:[1,0]
	v_pk_mul_f32 v[56:57], v[56:57], v[176:177] op_sel_hi:[1,0]
	v_pk_mul_f32 v[58:59], v[58:59], v[176:177] op_sel_hi:[1,0]
	v_pk_mul_f32 v[28:29], v[28:29], v[176:177] op_sel_hi:[1,0]
	v_pk_mul_f32 v[30:31], v[30:31], v[176:177] op_sel_hi:[1,0]
	v_pk_mul_f32 v[12:13], v[12:13], v[176:177] op_sel_hi:[1,0]
	v_pk_mul_f32 v[14:15], v[14:15], v[176:177] op_sel_hi:[1,0]
	ds_write_b128 v198, v[80:83]
	ds_write_b128 v198, v[56:59] offset:64
	ds_write_b128 v198, v[28:31] offset:128
	ds_write_b128 v198, v[12:15] offset:192
	s_waitcnt lgkmcnt(4)
	s_waitcnt vmcnt(8)
	v_pk_fma_f32 v[40:41], v[200:201], v[192:193], v[128:129]
	v_pk_fma_f32 v[42:43], v[202:203], v[194:195], v[130:131]
	v_pk_fma_f32 v[76:77], v[204:205], v[192:193], v[132:133]
	v_pk_fma_f32 v[78:79], v[206:207], v[194:195], v[134:135]
	v_pk_fma_f32 v[104:105], v[208:209], v[192:193], v[136:137]
	v_pk_fma_f32 v[106:107], v[210:211], v[194:195], v[138:139]
	v_pk_fma_f32 v[92:93], v[212:213], v[192:193], v[140:141]
	v_pk_fma_f32 v[94:95], v[214:215], v[194:195], v[142:143]
	v_fma_f32 v228, v40, v40, v228
	v_fma_f32 v228, v41, v41, v228
	v_fma_f32 v228, v42, v42, v228
	v_fma_f32 v228, v43, v43, v228
	v_fma_f32 v229, v76, v76, v229
	v_fma_f32 v229, v77, v77, v229
	v_fma_f32 v229, v78, v78, v229
	v_fma_f32 v229, v79, v79, v229
	v_fma_f32 v230, v104, v104, v230
	v_fma_f32 v230, v105, v105, v230
	v_fma_f32 v230, v106, v106, v230
	v_fma_f32 v230, v107, v107, v230
	v_fma_f32 v231, v92, v92, v231
	v_fma_f32 v231, v93, v93, v231
	v_fma_f32 v231, v94, v94, v231
	v_fma_f32 v231, v95, v95, v231
	s_nop 1
	s_add_u32 s36, s44, 0x80200
	s_addc_u32 s37, s45, 0
	global_load_dwordx4 v[128:131], v232, s[36:37]
	global_load_dwordx4 v[132:135], v233, s[36:37]
	global_load_dwordx4 v[136:139], v234, s[36:37]
	global_load_dwordx4 v[140:143], v235, s[36:37]
	ds_read_b128 v[184:187], v243 offset:1024
	ds_read_b128 v[188:191], v243 offset:1040
	s_waitcnt lgkmcnt(0)
	v_mov_b32_e32 v192, v184
	v_mov_b32_e32 v193, v186
	v_mov_b32_e32 v194, v188
	v_mov_b32_e32 v195, v190
	v_mov_b32_e32 v184, v185
	v_mov_b32_e32 v185, v187
	v_mov_b32_e32 v186, v189
	v_mov_b32_e32 v187, v191
	ds_read_b128 v[200:203], v242
	ds_read_b128 v[204:207], v242 offset:1088
	ds_read_b128 v[208:211], v242 offset:2176
	ds_read_b128 v[212:215], v242 offset:3264
	v_pk_mul_f32 v[72:73], v[72:73], v[178:179] op_sel_hi:[1,0]
	v_pk_mul_f32 v[74:75], v[74:75], v[178:179] op_sel_hi:[1,0]
	v_pk_mul_f32 v[44:45], v[44:45], v[178:179] op_sel_hi:[1,0]
	v_pk_mul_f32 v[46:47], v[46:47], v[178:179] op_sel_hi:[1,0]
	v_pk_mul_f32 v[24:25], v[24:25], v[178:179] op_sel_hi:[1,0]
	v_pk_mul_f32 v[26:27], v[26:27], v[178:179] op_sel_hi:[1,0]
	v_pk_mul_f32 v[8:9], v[8:9], v[178:179] op_sel_hi:[1,0]
	v_pk_mul_f32 v[10:11], v[10:11], v[178:179] op_sel_hi:[1,0]
	ds_write_b128 v198, v[72:75]
	ds_write_b128 v198, v[44:47] offset:64
	ds_write_b128 v198, v[24:27] offset:128
	ds_write_b128 v198, v[8:11] offset:192
	s_waitcnt lgkmcnt(4)
	s_waitcnt vmcnt(8)
	v_pk_fma_f32 v[80:81], v[200:201], v[192:193], v[144:145]
	v_pk_fma_f32 v[82:83], v[202:203], v[194:195], v[146:147]
	v_pk_fma_f32 v[56:57], v[204:205], v[192:193], v[148:149]
	v_pk_fma_f32 v[58:59], v[206:207], v[194:195], v[150:151]
	v_pk_fma_f32 v[28:29], v[208:209], v[192:193], v[152:153]
	v_pk_fma_f32 v[30:31], v[210:211], v[194:195], v[154:155]
	v_pk_fma_f32 v[12:13], v[212:213], v[192:193], v[156:157]
	v_pk_fma_f32 v[14:15], v[214:215], v[194:195], v[158:159]
	v_fma_f32 v216, v80, v80, v216
	v_fma_f32 v216, v81, v81, v216
	v_fma_f32 v216, v82, v82, v216
	v_fma_f32 v216, v83, v83, v216
	v_fma_f32 v217, v56, v56, v217
	v_fma_f32 v217, v57, v57, v217
	v_fma_f32 v217, v58, v58, v217
	v_fma_f32 v217, v59, v59, v217
	v_fma_f32 v218, v28, v28, v218
	v_fma_f32 v218, v29, v29, v218
	v_fma_f32 v218, v30, v30, v218
	v_fma_f32 v218, v31, v31, v218
	v_fma_f32 v219, v12, v12, v219
	v_fma_f32 v219, v13, v13, v219
	v_fma_f32 v219, v14, v14, v219
	v_fma_f32 v219, v15, v15, v219
	s_nop 1
	s_add_u32 s36, s44, 0x90200
	s_addc_u32 s37, s45, 0
	global_load_dwordx4 v[144:147], v232, s[36:37]
	global_load_dwordx4 v[148:151], v233, s[36:37]
	global_load_dwordx4 v[152:155], v234, s[36:37]
	global_load_dwordx4 v[156:159], v235, s[36:37]
	ds_read_b128 v[200:203], v242
	ds_read_b128 v[204:207], v242 offset:1088
	ds_read_b128 v[208:211], v242 offset:2176
	ds_read_b128 v[212:215], v242 offset:3264
	v_pk_mul_f32 v[68:69], v[68:69], v[180:181] op_sel_hi:[1,0]
	v_pk_mul_f32 v[70:71], v[70:71], v[180:181] op_sel_hi:[1,0]
	v_pk_mul_f32 v[36:37], v[36:37], v[180:181] op_sel_hi:[1,0]
	v_pk_mul_f32 v[38:39], v[38:39], v[180:181] op_sel_hi:[1,0]
	v_pk_mul_f32 v[20:21], v[20:21], v[180:181] op_sel_hi:[1,0]
	v_pk_mul_f32 v[22:23], v[22:23], v[180:181] op_sel_hi:[1,0]
	v_pk_mul_f32 v[4:5], v[4:5], v[180:181] op_sel_hi:[1,0]
	v_pk_mul_f32 v[6:7], v[6:7], v[180:181] op_sel_hi:[1,0]
	ds_write_b128 v198, v[68:71]
	ds_write_b128 v198, v[36:39] offset:64
	ds_write_b128 v198, v[20:23] offset:128
	ds_write_b128 v198, v[4:7] offset:192
	s_waitcnt lgkmcnt(4)
	s_waitcnt vmcnt(8)
	v_pk_fma_f32 v[72:73], v[200:201], v[192:193], v[160:161]
	v_pk_fma_f32 v[74:75], v[202:203], v[194:195], v[162:163]
	v_pk_fma_f32 v[44:45], v[204:205], v[192:193], v[164:165]
	v_pk_fma_f32 v[46:47], v[206:207], v[194:195], v[166:167]
	v_pk_fma_f32 v[24:25], v[208:209], v[192:193], v[168:169]
	v_pk_fma_f32 v[26:27], v[210:211], v[194:195], v[170:171]
	v_pk_fma_f32 v[8:9], v[212:213], v[192:193], v[172:173]
	v_pk_fma_f32 v[10:11], v[214:215], v[194:195], v[174:175]
	v_fma_f32 v220, v72, v72, v220
	v_fma_f32 v220, v73, v73, v220
	v_fma_f32 v220, v74, v74, v220
	v_fma_f32 v220, v75, v75, v220
	v_fma_f32 v221, v44, v44, v221
	v_fma_f32 v221, v45, v45, v221
	v_fma_f32 v221, v46, v46, v221
	v_fma_f32 v221, v47, v47, v221
	v_fma_f32 v222, v24, v24, v222
	v_fma_f32 v222, v25, v25, v222
	v_fma_f32 v222, v26, v26, v222
	v_fma_f32 v222, v27, v27, v222
	v_fma_f32 v223, v8, v8, v223
	v_fma_f32 v223, v9, v9, v223
	v_fma_f32 v223, v10, v10, v223
	v_fma_f32 v223, v11, v11, v223
	ds_read_b128 v[200:203], v242
	ds_read_b128 v[204:207], v242 offset:1088
	ds_read_b128 v[208:211], v242 offset:2176
	ds_read_b128 v[212:215], v242 offset:3264
	v_pk_mul_f32 v[64:65], v[64:65], v[182:183] op_sel_hi:[1,0]
	v_pk_mul_f32 v[66:67], v[66:67], v[182:183] op_sel_hi:[1,0]
	v_pk_mul_f32 v[32:33], v[32:33], v[182:183] op_sel_hi:[1,0]
	v_pk_mul_f32 v[34:35], v[34:35], v[182:183] op_sel_hi:[1,0]
	v_pk_mul_f32 v[16:17], v[16:17], v[182:183] op_sel_hi:[1,0]
	v_pk_mul_f32 v[18:19], v[18:19], v[182:183] op_sel_hi:[1,0]
	v_pk_mul_f32 v[0:1], v[0:1], v[182:183] op_sel_hi:[1,0]
	v_pk_mul_f32 v[2:3], v[2:3], v[182:183] op_sel_hi:[1,0]
	ds_write_b128 v198, v[64:67]
	ds_write_b128 v198, v[32:35] offset:64
	ds_write_b128 v198, v[16:19] offset:128
	ds_write_b128 v198, v[0:3] offset:192
	s_waitcnt lgkmcnt(4)
	s_waitcnt vmcnt(4)
	v_pk_fma_f32 v[68:69], v[200:201], v[192:193], v[128:129]
	v_pk_fma_f32 v[70:71], v[202:203], v[194:195], v[130:131]
	v_pk_fma_f32 v[36:37], v[204:205], v[192:193], v[132:133]
	v_pk_fma_f32 v[38:39], v[206:207], v[194:195], v[134:135]
	v_pk_fma_f32 v[20:21], v[208:209], v[192:193], v[136:137]
	v_pk_fma_f32 v[22:23], v[210:211], v[194:195], v[138:139]
	v_pk_fma_f32 v[4:5], v[212:213], v[192:193], v[140:141]
	v_pk_fma_f32 v[6:7], v[214:215], v[194:195], v[142:143]
	v_fma_f32 v224, v68, v68, v224
	v_fma_f32 v224, v69, v69, v224
	v_fma_f32 v224, v70, v70, v224
	v_fma_f32 v224, v71, v71, v224
	v_fma_f32 v225, v36, v36, v225
	v_fma_f32 v225, v37, v37, v225
	v_fma_f32 v225, v38, v38, v225
	v_fma_f32 v225, v39, v39, v225
	v_fma_f32 v226, v20, v20, v226
	v_fma_f32 v226, v21, v21, v226
	v_fma_f32 v226, v22, v22, v226
	v_fma_f32 v226, v23, v23, v226
	v_fma_f32 v227, v4, v4, v227
	v_fma_f32 v227, v5, v5, v227
	v_fma_f32 v227, v6, v6, v227
	v_fma_f32 v227, v7, v7, v227
	ds_read_b128 v[200:203], v242
	ds_read_b128 v[204:207], v242 offset:1088
	ds_read_b128 v[208:211], v242 offset:2176
	ds_read_b128 v[212:215], v242 offset:3264
	s_waitcnt lgkmcnt(0)
	s_waitcnt vmcnt(0)
	v_pk_fma_f32 v[64:65], v[200:201], v[192:193], v[144:145]
	v_pk_fma_f32 v[66:67], v[202:203], v[194:195], v[146:147]
	v_pk_fma_f32 v[32:33], v[204:205], v[192:193], v[148:149]
	v_pk_fma_f32 v[34:35], v[206:207], v[194:195], v[150:151]
	v_pk_fma_f32 v[16:17], v[208:209], v[192:193], v[152:153]
	v_pk_fma_f32 v[18:19], v[210:211], v[194:195], v[154:155]
	v_pk_fma_f32 v[0:1], v[212:213], v[192:193], v[156:157]
	v_pk_fma_f32 v[2:3], v[214:215], v[194:195], v[158:159]
	v_fma_f32 v228, v64, v64, v228
	v_fma_f32 v228, v65, v65, v228
	v_fma_f32 v228, v66, v66, v228
	v_fma_f32 v228, v67, v67, v228
	v_fma_f32 v229, v32, v32, v229
	v_fma_f32 v229, v33, v33, v229
	v_fma_f32 v229, v34, v34, v229
	v_fma_f32 v229, v35, v35, v229
	v_fma_f32 v230, v16, v16, v230
	v_fma_f32 v230, v17, v17, v230
	v_fma_f32 v230, v18, v18, v230
	v_fma_f32 v230, v19, v19, v230
	v_fma_f32 v231, v0, v0, v231
	v_fma_f32 v231, v1, v1, v231
	v_fma_f32 v231, v2, v2, v231
	v_fma_f32 v231, v3, v3, v231
	v_add_f32_dpp v216, v216, v216 row_ror:8 row_mask:0xf bank_mask:0xf
	v_add_f32_dpp v217, v217, v217 row_ror:8 row_mask:0xf bank_mask:0xf
	v_add_f32_dpp v218, v218, v218 row_ror:8 row_mask:0xf bank_mask:0xf
	v_add_f32_dpp v219, v219, v219 row_ror:8 row_mask:0xf bank_mask:0xf
	v_add_f32_dpp v220, v220, v220 row_ror:8 row_mask:0xf bank_mask:0xf
	v_add_f32_dpp v221, v221, v221 row_ror:8 row_mask:0xf bank_mask:0xf
	v_add_f32_dpp v222, v222, v222 row_ror:8 row_mask:0xf bank_mask:0xf
	v_add_f32_dpp v223, v223, v223 row_ror:8 row_mask:0xf bank_mask:0xf
	v_add_f32_dpp v224, v224, v224 row_ror:8 row_mask:0xf bank_mask:0xf
	v_add_f32_dpp v225, v225, v225 row_ror:8 row_mask:0xf bank_mask:0xf
	v_add_f32_dpp v226, v226, v226 row_ror:8 row_mask:0xf bank_mask:0xf
	v_add_f32_dpp v227, v227, v227 row_ror:8 row_mask:0xf bank_mask:0xf
	v_add_f32_dpp v228, v228, v228 row_ror:8 row_mask:0xf bank_mask:0xf
	v_add_f32_dpp v229, v229, v229 row_ror:8 row_mask:0xf bank_mask:0xf
	v_add_f32_dpp v230, v230, v230 row_ror:8 row_mask:0xf bank_mask:0xf
	v_add_f32_dpp v231, v231, v231 row_ror:8 row_mask:0xf bank_mask:0xf
	v_add_f32_dpp v216, v216, v216 row_ror:4 row_mask:0xf bank_mask:0xf
	v_add_f32_dpp v217, v217, v217 row_ror:4 row_mask:0xf bank_mask:0xf
	v_add_f32_dpp v218, v218, v218 row_ror:4 row_mask:0xf bank_mask:0xf
	v_add_f32_dpp v219, v219, v219 row_ror:4 row_mask:0xf bank_mask:0xf
	v_add_f32_dpp v220, v220, v220 row_ror:4 row_mask:0xf bank_mask:0xf
	v_add_f32_dpp v221, v221, v221 row_ror:4 row_mask:0xf bank_mask:0xf
	v_add_f32_dpp v222, v222, v222 row_ror:4 row_mask:0xf bank_mask:0xf
	v_add_f32_dpp v223, v223, v223 row_ror:4 row_mask:0xf bank_mask:0xf
	v_add_f32_dpp v224, v224, v224 row_ror:4 row_mask:0xf bank_mask:0xf
	v_add_f32_dpp v225, v225, v225 row_ror:4 row_mask:0xf bank_mask:0xf
	v_add_f32_dpp v226, v226, v226 row_ror:4 row_mask:0xf bank_mask:0xf
	v_add_f32_dpp v227, v227, v227 row_ror:4 row_mask:0xf bank_mask:0xf
	v_add_f32_dpp v228, v228, v228 row_ror:4 row_mask:0xf bank_mask:0xf
	v_add_f32_dpp v229, v229, v229 row_ror:4 row_mask:0xf bank_mask:0xf
	v_add_f32_dpp v230, v230, v230 row_ror:4 row_mask:0xf bank_mask:0xf
	v_add_f32_dpp v231, v231, v231 row_ror:4 row_mask:0xf bank_mask:0xf
	v_add_f32_dpp v216, v216, v216 row_ror:2 row_mask:0xf bank_mask:0xf
	v_add_f32_dpp v217, v217, v217 row_ror:2 row_mask:0xf bank_mask:0xf
	v_add_f32_dpp v218, v218, v218 row_ror:2 row_mask:0xf bank_mask:0xf
	v_add_f32_dpp v219, v219, v219 row_ror:2 row_mask:0xf bank_mask:0xf
	v_add_f32_dpp v220, v220, v220 row_ror:2 row_mask:0xf bank_mask:0xf
	v_add_f32_dpp v221, v221, v221 row_ror:2 row_mask:0xf bank_mask:0xf
	v_add_f32_dpp v222, v222, v222 row_ror:2 row_mask:0xf bank_mask:0xf
	v_add_f32_dpp v223, v223, v223 row_ror:2 row_mask:0xf bank_mask:0xf
	v_add_f32_dpp v224, v224, v224 row_ror:2 row_mask:0xf bank_mask:0xf
	v_add_f32_dpp v225, v225, v225 row_ror:2 row_mask:0xf bank_mask:0xf
	v_add_f32_dpp v226, v226, v226 row_ror:2 row_mask:0xf bank_mask:0xf
	v_add_f32_dpp v227, v227, v227 row_ror:2 row_mask:0xf bank_mask:0xf
	v_add_f32_dpp v228, v228, v228 row_ror:2 row_mask:0xf bank_mask:0xf
	v_add_f32_dpp v229, v229, v229 row_ror:2 row_mask:0xf bank_mask:0xf
	v_add_f32_dpp v230, v230, v230 row_ror:2 row_mask:0xf bank_mask:0xf
	v_add_f32_dpp v231, v231, v231 row_ror:2 row_mask:0xf bank_mask:0xf
	v_add_f32_dpp v216, v216, v216 row_ror:1 row_mask:0xf bank_mask:0xf
	v_add_f32_dpp v217, v217, v217 row_ror:1 row_mask:0xf bank_mask:0xf
	v_add_f32_dpp v218, v218, v218 row_ror:1 row_mask:0xf bank_mask:0xf
	v_add_f32_dpp v219, v219, v219 row_ror:1 row_mask:0xf bank_mask:0xf
	v_add_f32_dpp v220, v220, v220 row_ror:1 row_mask:0xf bank_mask:0xf
	v_add_f32_dpp v221, v221, v221 row_ror:1 row_mask:0xf bank_mask:0xf
	v_add_f32_dpp v222, v222, v222 row_ror:1 row_mask:0xf bank_mask:0xf
	v_add_f32_dpp v223, v223, v223 row_ror:1 row_mask:0xf bank_mask:0xf
	v_add_f32_dpp v224, v224, v224 row_ror:1 row_mask:0xf bank_mask:0xf
	v_add_f32_dpp v225, v225, v225 row_ror:1 row_mask:0xf bank_mask:0xf
	v_add_f32_dpp v226, v226, v226 row_ror:1 row_mask:0xf bank_mask:0xf
	v_add_f32_dpp v227, v227, v227 row_ror:1 row_mask:0xf bank_mask:0xf
	v_add_f32_dpp v228, v228, v228 row_ror:1 row_mask:0xf bank_mask:0xf
	v_add_f32_dpp v229, v229, v229 row_ror:1 row_mask:0xf bank_mask:0xf
	v_add_f32_dpp v230, v230, v230 row_ror:1 row_mask:0xf bank_mask:0xf
	v_add_f32_dpp v231, v231, v231 row_ror:1 row_mask:0xf bank_mask:0xf
	s_add_u32 s46, s42, 0x1000
	s_addc_u32 s47, s43, 0
	s_mov_b32 exec_lo, 0x10001
	s_mov_b32 exec_hi, 0x10001
	global_store_dword v244, v216, s[42:43]
	global_store_dword v244, v217, s[42:43] offset:128
	global_store_dword v244, v218, s[42:43] offset:256
	global_store_dword v244, v219, s[42:43] offset:384
	global_store_dword v244, v220, s[42:43] offset:512
	global_store_dword v244, v221, s[42:43] offset:640
	global_store_dword v244, v222, s[42:43] offset:768
	global_store_dword v244, v223, s[42:43] offset:896
	global_store_dword v244, v224, s[46:47]
	global_store_dword v244, v225, s[46:47] offset:128
	global_store_dword v244, v226, s[46:47] offset:256
	global_store_dword v244, v227, s[46:47] offset:384
	global_store_dword v244, v228, s[46:47] offset:512
	global_store_dword v244, v229, s[46:47] offset:640
	global_store_dword v244, v230, s[46:47] offset:768
	global_store_dword v244, v231, s[46:47] offset:896
	s_mov_b64 exec, -1
	s_waitcnt vmcnt(0)
	s_barrier
	s_cmp_lg_u32 s3, 0
	s_cbranch_scc1 .Lof_w
	s_mov_b64 s[36:37], exec
	s_mov_b64 exec, 1
	s_and_b32 s38, s85, 7
	s_lshl_b32 s38, s38, 8
	s_add_i32 s38, s38, 0xb8fc4e0
	v_mov_b32_e32 v200, s38
	v_mov_b32_e32 v201, 1
	global_atomic_add v200, v201, s[28:29]
	buffer_inv sc1
	s_mov_b32 s39, 0
.Lof_spin:
	global_load_dword v202, v200, s[28:29] sc1
	s_waitcnt vmcnt(0)
	v_cmp_le_u32_e32 vcc, 24, v202
	s_cbranch_vccnz .Lof_got
	s_sleep 1
	s_add_i32 s39, s39, 1
	s_cmp_lt_u32 s39, 0x8000
	s_cbranch_scc1 .Lof_spin
.Lof_got:
	s_waitcnt vmcnt(0)
	s_mov_b64 exec, s[36:37]
.Lof_w:
	s_barrier
	v_mbcnt_lo_u32_b32 v200, -1, 0
	v_mbcnt_hi_u32_b32 v200, -1, v200
	v_and_b32_e32 v201, 7, v200
	v_lshlrev_b32_e32 v201, 2, v201
	v_lshrrev_b32_e32 v202, 4, v200
	s_lshr_b32 s36, s3, 6
	s_and_b32 s38, s36, 3
	s_lshr_b32 s37, s36, 2
	s_lshl_b32 s40, s38, 10
	v_lshl_add_u32 v245, v202, 5, s40
	v_add_u32_e32 v245, v201, v245
	s_lshl_b32 s40, s96, 5
	s_add_u32 s44, s87, s40
	s_addc_u32 s45, s19, 0
	s_add_u32 s46, s44, 0x1000
	s_addc_u32 s47, s45, 0
	v_mov_b32_e32 v216, 0
	v_mov_b32_e32 v217, 0
	v_mov_b32_e32 v218, 0
	v_mov_b32_e32 v219, 0
	v_mov_b32_e32 v220, 0
	v_mov_b32_e32 v221, 0
	v_mov_b32_e32 v222, 0
	v_mov_b32_e32 v223, 0
	v_mov_b32_e32 v224, 0
	v_mov_b32_e32 v225, 0
	v_mov_b32_e32 v226, 0
	v_mov_b32_e32 v227, 0
	v_mov_b32_e32 v228, 0
	v_mov_b32_e32 v229, 0
	v_mov_b32_e32 v230, 0
	v_mov_b32_e32 v231, 0
	s_mov_b32 exec_lo, 0xff00ff
	s_mov_b32 exec_hi, 0xff00ff
	global_load_dword v216, v245, s[44:45]
	global_load_dword v217, v245, s[44:45] offset:128
	global_load_dword v218, v245, s[44:45] offset:256
	global_load_dword v219, v245, s[44:45] offset:384
	global_load_dword v220, v245, s[44:45] offset:512
	global_load_dword v221, v245, s[44:45] offset:640
	global_load_dword v222, v245, s[44:45] offset:768
	global_load_dword v223, v245, s[44:45] offset:896
	global_load_dword v224, v245, s[46:47]
	global_load_dword v225, v245, s[46:47] offset:128
	global_load_dword v226, v245, s[46:47] offset:256
	global_load_dword v227, v245, s[46:47] offset:384
	global_load_dword v228, v245, s[46:47] offset:512
	global_load_dword v229, v245, s[46:47] offset:640
	global_load_dword v230, v245, s[46:47] offset:768
	global_load_dword v231, v245, s[46:47] offset:896
	s_mov_b64 exec, -1
	v_readlane_b32 s40, v254, 39
	v_readlane_b32 s41, v254, 40
	v_and_b32_e32 v201, 15, v200
	s_lshl_b32 s36, s37, 8
	s_lshl_b32 s38, s94, 2
	s_add_i32 s36, s36, s38
	v_lshl_add_u32 v201, v201, 4, s36
	global_load_dwordx4 v[184:187], v201, s[40:41]
	global_load_dwordx4 v[188:191], v201, s[40:41] offset:512
	v_readlane_b32 s40, v254, 41
	v_readlane_b32 s41, v254, 42
	s_lshl_b32 s36, s96, 12
	s_add_u32 s36, s36, s38
	s_add_u32 s48, s40, s36
	s_addc_u32 s49, s41, 0
	v_mov_b32_e32 v203, 0x358637bd
	s_waitcnt vmcnt(2)
	v_add_f32_dpp v216, v216, v216 row_ror:8 row_mask:0xf bank_mask:0xf
	v_add_f32_dpp v217, v217, v217 row_ror:8 row_mask:0xf bank_mask:0xf
	v_add_f32_dpp v218, v218, v218 row_ror:8 row_mask:0xf bank_mask:0xf
	v_add_f32_dpp v219, v219, v219 row_ror:8 row_mask:0xf bank_mask:0xf
	v_add_f32_dpp v220, v220, v220 row_ror:8 row_mask:0xf bank_mask:0xf
	v_add_f32_dpp v221, v221, v221 row_ror:8 row_mask:0xf bank_mask:0xf
	v_add_f32_dpp v222, v222, v222 row_ror:8 row_mask:0xf bank_mask:0xf
	v_add_f32_dpp v223, v223, v223 row_ror:8 row_mask:0xf bank_mask:0xf
	v_add_f32_dpp v224, v224, v224 row_ror:8 row_mask:0xf bank_mask:0xf
	v_add_f32_dpp v225, v225, v225 row_ror:8 row_mask:0xf bank_mask:0xf
	v_add_f32_dpp v226, v226, v226 row_ror:8 row_mask:0xf bank_mask:0xf
	v_add_f32_dpp v227, v227, v227 row_ror:8 row_mask:0xf bank_mask:0xf
	v_add_f32_dpp v228, v228, v228 row_ror:8 row_mask:0xf bank_mask:0xf
	v_add_f32_dpp v229, v229, v229 row_ror:8 row_mask:0xf bank_mask:0xf
	v_add_f32_dpp v230, v230, v230 row_ror:8 row_mask:0xf bank_mask:0xf
	v_add_f32_dpp v231, v231, v231 row_ror:8 row_mask:0xf bank_mask:0xf
	v_add_f32_dpp v216, v216, v216 row_ror:4 row_mask:0xf bank_mask:0xf
	v_add_f32_dpp v217, v217, v217 row_ror:4 row_mask:0xf bank_mask:0xf
	v_add_f32_dpp v218, v218, v218 row_ror:4 row_mask:0xf bank_mask:0xf
	v_add_f32_dpp v219, v219, v219 row_ror:4 row_mask:0xf bank_mask:0xf
	v_add_f32_dpp v220, v220, v220 row_ror:4 row_mask:0xf bank_mask:0xf
	v_add_f32_dpp v221, v221, v221 row_ror:4 row_mask:0xf bank_mask:0xf
	v_add_f32_dpp v222, v222, v222 row_ror:4 row_mask:0xf bank_mask:0xf
	v_add_f32_dpp v223, v223, v223 row_ror:4 row_mask:0xf bank_mask:0xf
	v_add_f32_dpp v224, v224, v224 row_ror:4 row_mask:0xf bank_mask:0xf
	v_add_f32_dpp v225, v225, v225 row_ror:4 row_mask:0xf bank_mask:0xf
	v_add_f32_dpp v226, v226, v226 row_ror:4 row_mask:0xf bank_mask:0xf
	v_add_f32_dpp v227, v227, v227 row_ror:4 row_mask:0xf bank_mask:0xf
	v_add_f32_dpp v228, v228, v228 row_ror:4 row_mask:0xf bank_mask:0xf
	v_add_f32_dpp v229, v229, v229 row_ror:4 row_mask:0xf bank_mask:0xf
	v_add_f32_dpp v230, v230, v230 row_ror:4 row_mask:0xf bank_mask:0xf
	v_add_f32_dpp v231, v231, v231 row_ror:4 row_mask:0xf bank_mask:0xf
	v_add_f32_dpp v216, v216, v216 row_ror:2 row_mask:0xf bank_mask:0xf
	v_add_f32_dpp v217, v217, v217 row_ror:2 row_mask:0xf bank_mask:0xf
	v_add_f32_dpp v218, v218, v218 row_ror:2 row_mask:0xf bank_mask:0xf
	v_add_f32_dpp v219, v219, v219 row_ror:2 row_mask:0xf bank_mask:0xf
	v_add_f32_dpp v220, v220, v220 row_ror:2 row_mask:0xf bank_mask:0xf
	v_add_f32_dpp v221, v221, v221 row_ror:2 row_mask:0xf bank_mask:0xf
	v_add_f32_dpp v222, v222, v222 row_ror:2 row_mask:0xf bank_mask:0xf
	v_add_f32_dpp v223, v223, v223 row_ror:2 row_mask:0xf bank_mask:0xf
	v_add_f32_dpp v224, v224, v224 row_ror:2 row_mask:0xf bank_mask:0xf
	v_add_f32_dpp v225, v225, v225 row_ror:2 row_mask:0xf bank_mask:0xf
	v_add_f32_dpp v226, v226, v226 row_ror:2 row_mask:0xf bank_mask:0xf
	v_add_f32_dpp v227, v227, v227 row_ror:2 row_mask:0xf bank_mask:0xf
	v_add_f32_dpp v228, v228, v228 row_ror:2 row_mask:0xf bank_mask:0xf
	v_add_f32_dpp v229, v229, v229 row_ror:2 row_mask:0xf bank_mask:0xf
	v_add_f32_dpp v230, v230, v230 row_ror:2 row_mask:0xf bank_mask:0xf
	v_add_f32_dpp v231, v231, v231 row_ror:2 row_mask:0xf bank_mask:0xf
	v_add_f32_dpp v216, v216, v216 row_ror:1 row_mask:0xf bank_mask:0xf
	v_add_f32_dpp v217, v217, v217 row_ror:1 row_mask:0xf bank_mask:0xf
	v_add_f32_dpp v218, v218, v218 row_ror:1 row_mask:0xf bank_mask:0xf
	v_add_f32_dpp v219, v219, v219 row_ror:1 row_mask:0xf bank_mask:0xf
	v_add_f32_dpp v220, v220, v220 row_ror:1 row_mask:0xf bank_mask:0xf
	v_add_f32_dpp v221, v221, v221 row_ror:1 row_mask:0xf bank_mask:0xf
	v_add_f32_dpp v222, v222, v222 row_ror:1 row_mask:0xf bank_mask:0xf
	v_add_f32_dpp v223, v223, v223 row_ror:1 row_mask:0xf bank_mask:0xf
	v_add_f32_dpp v224, v224, v224 row_ror:1 row_mask:0xf bank_mask:0xf
	v_add_f32_dpp v225, v225, v225 row_ror:1 row_mask:0xf bank_mask:0xf
	v_add_f32_dpp v226, v226, v226 row_ror:1 row_mask:0xf bank_mask:0xf
	v_add_f32_dpp v227, v227, v227 row_ror:1 row_mask:0xf bank_mask:0xf
	v_add_f32_dpp v228, v228, v228 row_ror:1 row_mask:0xf bank_mask:0xf
	v_add_f32_dpp v229, v229, v229 row_ror:1 row_mask:0xf bank_mask:0xf
	v_add_f32_dpp v230, v230, v230 row_ror:1 row_mask:0xf bank_mask:0xf
	v_add_f32_dpp v231, v231, v231 row_ror:1 row_mask:0xf bank_mask:0xf
	v_fmamk_f32 v216, v216, 0x3a800000, v203
	v_fmamk_f32 v217, v217, 0x3a800000, v203
	v_fmamk_f32 v218, v218, 0x3a800000, v203
	v_fmamk_f32 v219, v219, 0x3a800000, v203
	v_fmamk_f32 v220, v220, 0x3a800000, v203
	v_fmamk_f32 v221, v221, 0x3a800000, v203
	v_fmamk_f32 v222, v222, 0x3a800000, v203
	v_fmamk_f32 v223, v223, 0x3a800000, v203
	v_fmamk_f32 v224, v224, 0x3a800000, v203
	v_fmamk_f32 v225, v225, 0x3a800000, v203
	v_fmamk_f32 v226, v226, 0x3a800000, v203
	v_fmamk_f32 v227, v227, 0x3a800000, v203
	v_fmamk_f32 v228, v228, 0x3a800000, v203
	v_fmamk_f32 v229, v229, 0x3a800000, v203
	v_fmamk_f32 v230, v230, 0x3a800000, v203
	v_fmamk_f32 v231, v231, 0x3a800000, v203
	v_rsq_f32_e32 v216, v216
	v_rsq_f32_e32 v217, v217
	v_rsq_f32_e32 v218, v218
	v_rsq_f32_e32 v219, v219
	v_rsq_f32_e32 v220, v220
	v_rsq_f32_e32 v221, v221
	v_rsq_f32_e32 v222, v222
	v_rsq_f32_e32 v223, v223
	v_rsq_f32_e32 v224, v224
	v_rsq_f32_e32 v225, v225
	v_rsq_f32_e32 v226, v226
	v_rsq_f32_e32 v227, v227
	v_rsq_f32_e32 v228, v228
	v_rsq_f32_e32 v229, v229
	v_rsq_f32_e32 v230, v230
	v_rsq_f32_e32 v231, v231
	s_waitcnt vmcnt(0)
	s_add_u32 s38, s48, 0x0
	s_addc_u32 s39, s49, 0
	v_mul_f32_e32 v48, v48, v216
	v_mul_f32_e32 v49, v49, v216
	v_mul_f32_e32 v50, v50, v216
	v_mul_f32_e32 v51, v51, v216
	v_pk_mul_f32 v[48:49], v[48:49], v[184:185]
	v_pk_mul_f32 v[50:51], v[50:51], v[186:187]
	v_mul_f32_e32 v116, v116, v217
	v_mul_f32_e32 v117, v117, v217
	v_mul_f32_e32 v118, v118, v217
	v_mul_f32_e32 v119, v119, v217
	v_pk_mul_f32 v[116:117], v[116:117], v[184:185]
	v_pk_mul_f32 v[118:119], v[118:119], v[186:187]
	v_mul_f32_e32 v124, v124, v218
	v_mul_f32_e32 v125, v125, v218
	v_mul_f32_e32 v126, v126, v218
	v_mul_f32_e32 v127, v127, v218
	v_pk_mul_f32 v[124:125], v[124:125], v[184:185]
	v_pk_mul_f32 v[126:127], v[126:127], v[186:187]
	v_mul_f32_e32 v108, v108, v219
	v_mul_f32_e32 v109, v109, v219
	v_mul_f32_e32 v110, v110, v219
	v_mul_f32_e32 v111, v111, v219
	v_pk_mul_f32 v[108:109], v[108:109], v[184:185]
	v_pk_mul_f32 v[110:111], v[110:111], v[186:187]
	global_store_dwordx4 v232, v[48:51], s[38:39]
	global_store_dwordx4 v233, v[116:119], s[38:39]
	global_store_dwordx4 v234, v[124:127], s[38:39]
	global_store_dwordx4 v235, v[108:111], s[38:39]
	s_add_u32 s38, s48, 0x10000
	s_addc_u32 s39, s49, 0
	v_mul_f32_e32 v60, v60, v220
	v_mul_f32_e32 v61, v61, v220
	v_mul_f32_e32 v62, v62, v220
	v_mul_f32_e32 v63, v63, v220
	v_pk_mul_f32 v[60:61], v[60:61], v[184:185]
	v_pk_mul_f32 v[62:63], v[62:63], v[186:187]
	v_mul_f32_e32 v88, v88, v221
	v_mul_f32_e32 v89, v89, v221
	v_mul_f32_e32 v90, v90, v221
	v_mul_f32_e32 v91, v91, v221
	v_pk_mul_f32 v[88:89], v[88:89], v[184:185]
	v_pk_mul_f32 v[90:91], v[90:91], v[186:187]
	v_mul_f32_e32 v120, v120, v222
	v_mul_f32_e32 v121, v121, v222
	v_mul_f32_e32 v122, v122, v222
	v_mul_f32_e32 v123, v123, v222
	v_pk_mul_f32 v[120:121], v[120:121], v[184:185]
	v_pk_mul_f32 v[122:123], v[122:123], v[186:187]
	v_mul_f32_e32 v100, v100, v223
	v_mul_f32_e32 v101, v101, v223
	v_mul_f32_e32 v102, v102, v223
	v_mul_f32_e32 v103, v103, v223
	v_pk_mul_f32 v[100:101], v[100:101], v[184:185]
	v_pk_mul_f32 v[102:103], v[102:103], v[186:187]
	global_store_dwordx4 v232, v[60:63], s[38:39]
	global_store_dwordx4 v233, v[88:91], s[38:39]
	global_store_dwordx4 v234, v[120:123], s[38:39]
	global_store_dwordx4 v235, v[100:103], s[38:39]
	s_add_u32 s38, s48, 0x80000
	s_addc_u32 s39, s49, 0
	v_mul_f32_e32 v52, v52, v224
	v_mul_f32_e32 v53, v53, v224
	v_mul_f32_e32 v54, v54, v224
	v_mul_f32_e32 v55, v55, v224
	v_pk_mul_f32 v[52:53], v[52:53], v[184:185]
	v_pk_mul_f32 v[54:55], v[54:55], v[186:187]
	v_mul_f32_e32 v84, v84, v225
	v_mul_f32_e32 v85, v85, v225
	v_mul_f32_e32 v86, v86, v225
	v_mul_f32_e32 v87, v87, v225
	v_pk_mul_f32 v[84:85], v[84:85], v[184:185]
	v_pk_mul_f32 v[86:87], v[86:87], v[186:187]
	v_mul_f32_e32 v112, v112, v226
	v_mul_f32_e32 v113, v113, v226
	v_mul_f32_e32 v114, v114, v226
	v_mul_f32_e32 v115, v115, v226
	v_pk_mul_f32 v[112:113], v[112:113], v[184:185]
	v_pk_mul_f32 v[114:115], v[114:115], v[186:187]
	v_mul_f32_e32 v96, v96, v227
	v_mul_f32_e32 v97, v97, v227
	v_mul_f32_e32 v98, v98, v227
	v_mul_f32_e32 v99, v99, v227
	v_pk_mul_f32 v[96:97], v[96:97], v[184:185]
	v_pk_mul_f32 v[98:99], v[98:99], v[186:187]
	global_store_dwordx4 v232, v[52:55], s[38:39]
	global_store_dwordx4 v233, v[84:87], s[38:39]
	global_store_dwordx4 v234, v[112:115], s[38:39]
	global_store_dwordx4 v235, v[96:99], s[38:39]
	s_add_u32 s38, s48, 0x90000
	s_addc_u32 s39, s49, 0
	v_mul_f32_e32 v40, v40, v228
	v_mul_f32_e32 v41, v41, v228
	v_mul_f32_e32 v42, v42, v228
	v_mul_f32_e32 v43, v43, v228
	v_pk_mul_f32 v[40:41], v[40:41], v[184:185]
	v_pk_mul_f32 v[42:43], v[42:43], v[186:187]
	v_mul_f32_e32 v76, v76, v229
	v_mul_f32_e32 v77, v77, v229
	v_mul_f32_e32 v78, v78, v229
	v_mul_f32_e32 v79, v79, v229
	v_pk_mul_f32 v[76:77], v[76:77], v[184:185]
	v_pk_mul_f32 v[78:79], v[78:79], v[186:187]
	v_mul_f32_e32 v104, v104, v230
	v_mul_f32_e32 v105, v105, v230
	v_mul_f32_e32 v106, v106, v230
	v_mul_f32_e32 v107, v107, v230
	v_pk_mul_f32 v[104:105], v[104:105], v[184:185]
	v_pk_mul_f32 v[106:107], v[106:107], v[186:187]
	v_mul_f32_e32 v92, v92, v231
	v_mul_f32_e32 v93, v93, v231
	v_mul_f32_e32 v94, v94, v231
	v_mul_f32_e32 v95, v95, v231
	v_pk_mul_f32 v[92:93], v[92:93], v[184:185]
	v_pk_mul_f32 v[94:95], v[94:95], v[186:187]
	global_store_dwordx4 v232, v[40:43], s[38:39]
	global_store_dwordx4 v233, v[76:79], s[38:39]
	global_store_dwordx4 v234, v[104:107], s[38:39]
	global_store_dwordx4 v235, v[92:95], s[38:39]
	s_add_u32 s38, s48, 0x200
	s_addc_u32 s39, s49, 0
	v_mul_f32_e32 v80, v80, v216
	v_mul_f32_e32 v81, v81, v216
	v_mul_f32_e32 v82, v82, v216
	v_mul_f32_e32 v83, v83, v216
	v_pk_mul_f32 v[80:81], v[80:81], v[188:189]
	v_pk_mul_f32 v[82:83], v[82:83], v[190:191]
	v_mul_f32_e32 v56, v56, v217
	v_mul_f32_e32 v57, v57, v217
	v_mul_f32_e32 v58, v58, v217
	v_mul_f32_e32 v59, v59, v217
	v_pk_mul_f32 v[56:57], v[56:57], v[188:189]
	v_pk_mul_f32 v[58:59], v[58:59], v[190:191]
	v_mul_f32_e32 v28, v28, v218
	v_mul_f32_e32 v29, v29, v218
	v_mul_f32_e32 v30, v30, v218
	v_mul_f32_e32 v31, v31, v218
	v_pk_mul_f32 v[28:29], v[28:29], v[188:189]
	v_pk_mul_f32 v[30:31], v[30:31], v[190:191]
	v_mul_f32_e32 v12, v12, v219
	v_mul_f32_e32 v13, v13, v219
	v_mul_f32_e32 v14, v14, v219
	v_mul_f32_e32 v15, v15, v219
	v_pk_mul_f32 v[12:13], v[12:13], v[188:189]
	v_pk_mul_f32 v[14:15], v[14:15], v[190:191]
	global_store_dwordx4 v232, v[80:83], s[38:39]
	global_store_dwordx4 v233, v[56:59], s[38:39]
	global_store_dwordx4 v234, v[28:31], s[38:39]
	global_store_dwordx4 v235, v[12:15], s[38:39]
	s_add_u32 s38, s48, 0x10200
	s_addc_u32 s39, s49, 0
	v_mul_f32_e32 v72, v72, v220
	v_mul_f32_e32 v73, v73, v220
	v_mul_f32_e32 v74, v74, v220
	v_mul_f32_e32 v75, v75, v220
	v_pk_mul_f32 v[72:73], v[72:73], v[188:189]
	v_pk_mul_f32 v[74:75], v[74:75], v[190:191]
	v_mul_f32_e32 v44, v44, v221
	v_mul_f32_e32 v45, v45, v221
	v_mul_f32_e32 v46, v46, v221
	v_mul_f32_e32 v47, v47, v221
	v_pk_mul_f32 v[44:45], v[44:45], v[188:189]
	v_pk_mul_f32 v[46:47], v[46:47], v[190:191]
	v_mul_f32_e32 v24, v24, v222
	v_mul_f32_e32 v25, v25, v222
	v_mul_f32_e32 v26, v26, v222
	v_mul_f32_e32 v27, v27, v222
	v_pk_mul_f32 v[24:25], v[24:25], v[188:189]
	v_pk_mul_f32 v[26:27], v[26:27], v[190:191]
	v_mul_f32_e32 v8, v8, v223
	v_mul_f32_e32 v9, v9, v223
	v_mul_f32_e32 v10, v10, v223
	v_mul_f32_e32 v11, v11, v223
	v_pk_mul_f32 v[8:9], v[8:9], v[188:189]
	v_pk_mul_f32 v[10:11], v[10:11], v[190:191]
	global_store_dwordx4 v232, v[72:75], s[38:39]
	global_store_dwordx4 v233, v[44:47], s[38:39]
	global_store_dwordx4 v234, v[24:27], s[38:39]
	global_store_dwordx4 v235, v[8:11], s[38:39]
	s_add_u32 s38, s48, 0x80200
	s_addc_u32 s39, s49, 0
	v_mul_f32_e32 v68, v68, v224
	v_mul_f32_e32 v69, v69, v224
	v_mul_f32_e32 v70, v70, v224
	v_mul_f32_e32 v71, v71, v224
	v_pk_mul_f32 v[68:69], v[68:69], v[188:189]
	v_pk_mul_f32 v[70:71], v[70:71], v[190:191]
	v_mul_f32_e32 v36, v36, v225
	v_mul_f32_e32 v37, v37, v225
	v_mul_f32_e32 v38, v38, v225
	v_mul_f32_e32 v39, v39, v225
	v_pk_mul_f32 v[36:37], v[36:37], v[188:189]
	v_pk_mul_f32 v[38:39], v[38:39], v[190:191]
	v_mul_f32_e32 v20, v20, v226
	v_mul_f32_e32 v21, v21, v226
	v_mul_f32_e32 v22, v22, v226
	v_mul_f32_e32 v23, v23, v226
	v_pk_mul_f32 v[20:21], v[20:21], v[188:189]
	v_pk_mul_f32 v[22:23], v[22:23], v[190:191]
	v_mul_f32_e32 v4, v4, v227
	v_mul_f32_e32 v5, v5, v227
	v_mul_f32_e32 v6, v6, v227
	v_mul_f32_e32 v7, v7, v227
	v_pk_mul_f32 v[4:5], v[4:5], v[188:189]
	v_pk_mul_f32 v[6:7], v[6:7], v[190:191]
	global_store_dwordx4 v232, v[68:71], s[38:39]
	global_store_dwordx4 v233, v[36:39], s[38:39]
	global_store_dwordx4 v234, v[20:23], s[38:39]
	global_store_dwordx4 v235, v[4:7], s[38:39]
	s_add_u32 s38, s48, 0x90200
	s_addc_u32 s39, s49, 0
	v_mul_f32_e32 v64, v64, v228
	v_mul_f32_e32 v65, v65, v228
	v_mul_f32_e32 v66, v66, v228
	v_mul_f32_e32 v67, v67, v228
	v_pk_mul_f32 v[64:65], v[64:65], v[188:189]
	v_pk_mul_f32 v[66:67], v[66:67], v[190:191]
	v_mul_f32_e32 v32, v32, v229
	v_mul_f32_e32 v33, v33, v229
	v_mul_f32_e32 v34, v34, v229
	v_mul_f32_e32 v35, v35, v229
	v_pk_mul_f32 v[32:33], v[32:33], v[188:189]
	v_pk_mul_f32 v[34:35], v[34:35], v[190:191]
	v_mul_f32_e32 v16, v16, v230
	v_mul_f32_e32 v17, v17, v230
	v_mul_f32_e32 v18, v18, v230
	v_mul_f32_e32 v19, v19, v230
	v_pk_mul_f32 v[16:17], v[16:17], v[188:189]
	v_pk_mul_f32 v[18:19], v[18:19], v[190:191]
	v_mul_f32_e32 v0, v0, v231
	v_mul_f32_e32 v1, v1, v231
	v_mul_f32_e32 v2, v2, v231
	v_mul_f32_e32 v3, v3, v231
	v_pk_mul_f32 v[0:1], v[0:1], v[188:189]
	v_pk_mul_f32 v[2:3], v[2:3], v[190:191]
	global_store_dwordx4 v232, v[64:67], s[38:39]
	global_store_dwordx4 v233, v[32:35], s[38:39]
	global_store_dwordx4 v234, v[16:19], s[38:39]
	global_store_dwordx4 v235, v[0:3], s[38:39]
	s_endpgm
